# SEAM4 fast path without L2 write-back; SEAM5 fast path: the XCC's first arriver writes back L2 before bumping the WAR counter
# speedup vs baseline: 1.0175x; 1.0059x over previous
; __device__ __forceinline__ unsigned xb_ld(unsigned* p)              { return __hip_atomic_load(p, __ATOMIC_RELAXED, __HIP_MEMORY_SCOPE_AGENT); }
; __device__ __forceinline__ unsigned xb_add(unsigned* p, unsigned v) { return __hip_atomic_fetch_add(p, v, __ATOMIC_RELAXED, __HIP_MEMORY_SCOPE_AGENT); }
; #define XB_SPIN(cond, bar) do { unsigned _sp = 0; while (cond) { __builtin_amdgcn_s_sleep(1); \
;     if ((++_sp & 255u) == 0u) { if (xb_ld(&(bar)[XB_TMO])) break; if (_sp > XB_SPIN_CAP) { atomicAdd(&(bar)[XB_TMO], 1u); break; } } } } while (0)
; __device__ __forceinline__ void xcd_barrier(const XcdBarrier& b) {
;     asm volatile("s_waitcnt vmcnt(0)" ::: "memory");
;     __syncthreads();
;     if (threadIdx.x == 0) {
;         unsigned* bar = b.bar;
;         __builtin_amdgcn_s_waitcnt(0);
;         unsigned nloc = b.st[0], nx = b.st[1];
;         if (nloc == 0u) { xcd_barrier_complete(bar, b.x, nloc, nx); b.st[0] = nloc; b.st[1] = nx; }
;         const unsigned old = xb_add(&bar[XB_XSUB(b.x)], 1u);
;         const unsigned gen = old / nloc;
;         if (old + 1u == (gen + 1u) * nloc) {
;             __builtin_amdgcn_fence(__ATOMIC_RELEASE, "agent");
;             asm volatile("s_waitcnt vmcnt(0)" ::: "memory");
;             const unsigned og = xb_add(&bar[XB_TOP], 1u);
;             const unsigned tg = og / nx;
;             if (og + 1u == (tg + 1u) * nx) xb_add(&bar[XB_TOPGEN], 1u);
;             else XB_SPIN(xb_ld(&bar[XB_TOPGEN]) == tg, bar);
;             __builtin_amdgcn_fence(__ATOMIC_ACQUIRE, "agent");
;             xb_add(&bar[XB_XGEN(b.x)], 1u);
;             asm volatile("s_waitcnt vmcnt(0)" ::: "memory");
;         } else {
;             XB_SPIN(xb_ld(&bar[XB_XGEN(b.x)]) == gen, bar);
;             __builtin_amdgcn_fence(__ATOMIC_ACQUIRE, "agent");
;             asm volatile("s_waitcnt vmcnt(0)" ::: "memory");
.LBB0_532:
	s_cmp_gt_i32 s83, 5
	s_cselect_b64 s[0:1], -1, 0
	s_and_b64 s[4:5], s[84:85], s[0:1]
	s_andn2_b64 vcc, exec, s[4:5]
	s_cbranch_vccnz .LBB0_586
	s_waitcnt vmcnt(0)
	s_waitcnt vmcnt(0) lgkmcnt(0)
	s_barrier
	s_mov_b64 s[4:5], exec
	v_readlane_b32 s6, v248, 2
	v_readlane_b32 s7, v248, 3
	s_and_b64 s[6:7], s[4:5], s[6:7]
	s_mov_b64 exec, s[6:7]
	s_cbranch_execz .LBB0_585
	v_mov_b32_e32 v0, 0x27e08
	ds_read_b32 v2, v0
	v_readlane_b32 s10, v248, 0
	v_readlane_b32 s11, v248, 1
	s_lshl_b32 s6, s3, 8
	v_mov_b32_e32 v4, 1
	s_add_u32 s6, s10, s6
	s_addc_u32 s7, s11, 0
	v_mov_b32_e32 v13, 0x3900
	s_waitcnt lgkmcnt(0)
	v_readfirstlane_b32 s8, v2
	s_nop 3
	s_cmp_eq_u32 s8, 0
	s_cbranch_scc1 .Ls4_slowpre
	v_mov_b32_e32 v5, 0x1000
	global_atomic_add v6, v5, v4, s[6:7] offset:1024 sc0
	v_mov_b32_e32 v5, 0x2000
	s_mov_b32 s99, 0
	s_waitcnt vmcnt(0)
	v_lshrrev_b32_e32 v7, 5, v6
	v_and_b32_e32 v8, 31, v6
	v_cmp_eq_u32_e32 vcc, 31, v8
	s_cbranch_vccz .Ls4_spin
	global_atomic_add v5, v4, s[6:7] offset:1024
	s_branch .Ls4_rel

; __device__ __forceinline__ unsigned xb_ld(unsigned* p)              { return __hip_atomic_load(p, __ATOMIC_RELAXED, __HIP_MEMORY_SCOPE_AGENT); }
; __device__ __forceinline__ void xcd_barrier_complete(unsigned* bar, unsigned x, unsigned& nloc, unsigned& nx) {
;     const unsigned G = gridDim.x * gridDim.y * gridDim.z;
;     unsigned sum, cnt, mine, sp = 0u;
;     for (;;) {
;         sum = 0u; cnt = 0u; mine = 0u;
; #pragma unroll
;         for (unsigned j = 0; j < 16; ++j) { const unsigned c = xb_ld(&bar[XB_XCNT(j)]); sum += c; cnt += (c > 0u) ? 1u : 0u; mine = (j == x) ? c : mine; }
;         if (sum == G) break;
;         __builtin_amdgcn_s_sleep(1);
;         if ((++sp & 255u) == 0u) { if (xb_ld(&bar[XB_TMO])) break; if (sp > XB_SPIN_CAP) { atomicAdd(&bar[XB_TMO], 1u); break; } }
;     }
;     nloc = mine > 0u ? mine : 1u; nx = cnt > 0u ? cnt : 1u;
; }
; __device__ __forceinline__ void xcd_barrier(const XcdBarrier& b) {
;     asm volatile("s_waitcnt vmcnt(0)" ::: "memory");
;     __syncthreads();
;     if (threadIdx.x == 0) {
;         unsigned* bar = b.bar;
;         __builtin_amdgcn_s_waitcnt(0);
;         unsigned nloc = b.st[0], nx = b.st[1];
;         if (nloc == 0u) { xcd_barrier_complete(bar, b.x, nloc, nx); b.st[0] = nloc; b.st[1] = nx; }
.Ls4_slowpre:
.Ls4_slow:
	s_add_i32 s6, 0, 0x27e00
	v_mov_b32_e32 v0, s6
	s_waitcnt vmcnt(0) expcnt(0) lgkmcnt(0)
	ds_read_b32 v2, v0
	s_add_i32 s6, 0, 0x27e04
	v_mov_b32_e32 v0, s6
	ds_read_b32 v0, v0
	s_waitcnt lgkmcnt(1)
	v_cmp_ne_u32_e32 vcc, 0, v2
	s_cbranch_vccnz .LBB0_549
	s_add_u32 s6, s78, 0x1f00200
	s_addc_u32 s7, s79, 0
	s_add_u32 s8, s78, 0x1f00400
	s_addc_u32 s9, s79, 0
	s_add_u32 s10, s78, 0x1f00500
	s_addc_u32 s11, s79, 0
	s_add_u32 s12, s78, 0x1f00600
	s_addc_u32 s13, s79, 0
	s_add_u32 s14, s78, 0x1f00700
	s_addc_u32 s15, s79, 0
	s_add_u32 s16, s78, 0x1f00800
	s_addc_u32 s17, s79, 0
	s_add_u32 s18, s78, 0x1f00900
	s_addc_u32 s19, s79, 0
	s_add_u32 s20, s78, 0x1f00a00
	s_addc_u32 s21, s79, 0
	s_add_u32 s22, s78, 0x1f00b00
	s_addc_u32 s23, s79, 0
	s_add_u32 s24, s78, 0x1f00c00
	s_addc_u32 s25, s79, 0
	s_add_u32 s26, s78, 0x1f00d00
	s_addc_u32 s27, s79, 0
	s_add_u32 s28, s78, 0x1f00e00
	s_addc_u32 s29, s79, 0
	s_add_u32 s30, s78, 0x1f00f00
	s_addc_u32 s31, s79, 0
	s_add_u32 s34, s78, 0x1f01000
	s_addc_u32 s35, s79, 0
	s_add_u32 s36, s78, 0x1f01100
	s_addc_u32 s37, s79, 0
	s_add_u32 s38, s78, 0x1f01200
	s_addc_u32 s39, s79, 0
	s_mul_i32 s48, s81, s33
	s_add_u32 s40, s78, 0x1f01300
	s_mul_i32 s48, s48, s80
	s_addc_u32 s41, s79, 0
	s_mov_b32 s49, 1
	v_mov_b32_e32 v16, 0
	s_branch .LBB0_537

; __device__ __forceinline__ unsigned xb_ld(unsigned* p)              { return __hip_atomic_load(p, __ATOMIC_RELAXED, __HIP_MEMORY_SCOPE_AGENT); }
; __device__ __forceinline__ unsigned xb_add(unsigned* p, unsigned v) { return __hip_atomic_fetch_add(p, v, __ATOMIC_RELAXED, __HIP_MEMORY_SCOPE_AGENT); }
; #define XB_SPIN(cond, bar) do { unsigned _sp = 0; while (cond) { __builtin_amdgcn_s_sleep(1); \
;     if ((++_sp & 255u) == 0u) { if (xb_ld(&(bar)[XB_TMO])) break; if (_sp > XB_SPIN_CAP) { atomicAdd(&(bar)[XB_TMO], 1u); break; } } } } while (0)
; __device__ __forceinline__ void xcd_barrier(const XcdBarrier& b) {
;     asm volatile("s_waitcnt vmcnt(0)" ::: "memory");
;     __syncthreads();
;     if (threadIdx.x == 0) {
;         unsigned* bar = b.bar;
;         __builtin_amdgcn_s_waitcnt(0);
;         unsigned nloc = b.st[0], nx = b.st[1];
;         if (nloc == 0u) { xcd_barrier_complete(bar, b.x, nloc, nx); b.st[0] = nloc; b.st[1] = nx; }
;         const unsigned old = xb_add(&bar[XB_XSUB(b.x)], 1u);
;         const unsigned gen = old / nloc;
;         if (old + 1u == (gen + 1u) * nloc) {
;             __builtin_amdgcn_fence(__ATOMIC_RELEASE, "agent");
;             asm volatile("s_waitcnt vmcnt(0)" ::: "memory");
;             const unsigned og = xb_add(&bar[XB_TOP], 1u);
;             const unsigned tg = og / nx;
;             if (og + 1u == (tg + 1u) * nx) xb_add(&bar[XB_TOPGEN], 1u);
;             else XB_SPIN(xb_ld(&bar[XB_TOPGEN]) == tg, bar);
;             __builtin_amdgcn_fence(__ATOMIC_ACQUIRE, "agent");
;             xb_add(&bar[XB_XGEN(b.x)], 1u);
;             asm volatile("s_waitcnt vmcnt(0)" ::: "memory");
;         } else {
;             XB_SPIN(xb_ld(&bar[XB_XGEN(b.x)]) == gen, bar);
;             __builtin_amdgcn_fence(__ATOMIC_ACQUIRE, "agent");
;             asm volatile("s_waitcnt vmcnt(0)" ::: "memory");
.LBB0_611:
	s_cmp_gt_i32 s83, 6
	s_cselect_b64 s[0:1], -1, 0
	s_and_b64 s[4:5], s[4:5], s[0:1]
	s_andn2_b64 vcc, exec, s[4:5]
	s_cbranch_vccnz .LBB0_665
	s_waitcnt vmcnt(0)
	s_waitcnt vmcnt(0) lgkmcnt(0)
	s_barrier
	s_mov_b64 s[4:5], exec
	v_readlane_b32 s6, v248, 2
	v_readlane_b32 s7, v248, 3
	s_and_b64 s[6:7], s[4:5], s[6:7]
	s_mov_b64 exec, s[6:7]
	s_cbranch_execz .LBB0_664
	v_mov_b32_e32 v0, 0x27e08
	ds_read_b32 v2, v0
	v_readlane_b32 s10, v248, 0
	v_readlane_b32 s11, v248, 1
	s_lshl_b32 s6, s3, 8
	v_mov_b32_e32 v4, 1
	s_add_u32 s6, s10, s6
	s_addc_u32 s7, s11, 0
	v_mov_b32_e32 v13, 0x3900
	s_waitcnt lgkmcnt(0)
	v_readfirstlane_b32 s8, v2
	s_nop 3
	s_cmp_eq_u32 s8, 0
	s_cbranch_scc1 .Ls5_slowpre
	v_mov_b32_e32 v5, 0x1000
	global_atomic_add v6, v5, v4, s[6:7] offset:1024 sc0
	v_mov_b32_e32 v5, 0x2000
	s_mov_b32 s99, 0
	s_waitcnt vmcnt(0)
	v_lshrrev_b32_e32 v7, 5, v6
	v_and_b32_e32 v8, 31, v6
	v_cmp_eq_u32_e32 vcc, 0, v8
	s_cbranch_vccz .Ls5_nb
	buffer_wbl2 sc1
	s_waitcnt vmcnt(0)
.Ls5_nb:
	global_atomic_add v13, v4, s[10:11]
	v_cmp_eq_u32_e32 vcc, 31, v8
	s_cbranch_vccz .Ls5_spin
	global_atomic_add v5, v4, s[6:7] offset:1024
	s_branch .Ls5_rel

; __device__ __forceinline__ unsigned xb_add(unsigned* p, unsigned v) { return __hip_atomic_fetch_add(p, v, __ATOMIC_RELAXED, __HIP_MEMORY_SCOPE_AGENT); }
; __device__ __forceinline__ void xcd_barrier(const XcdBarrier& b) {
;     ...
;         unsigned nloc = b.st[0], nx = b.st[1];
;         if (nloc == 0u) { xcd_barrier_complete(bar, b.x, nloc, nx); b.st[0] = nloc; b.st[1] = nx; }
;         const unsigned old = xb_add(&bar[XB_XSUB(b.x)], 1u);
.Ls5_slowpre:
	global_atomic_add v13, v4, s[10:11]
